# P8 gate epilogue: row rinv pre-scaled by -log2e, one multiply per sigmoid argument instead of two
# baseline (speedup 1.0000x reference)
.LBB0_1145:
	s_waitcnt vmcnt(0)
	v_fmamk_f32 v218, v218, 0x3a800000, v228
	v_mul_f32_e32 v219, 0x4b800000, v218
	v_cmp_gt_f32_e32 vcc, s69, v218
	s_lshl_b32 s8, s50, 2
	s_or_b32 s8, s8, s64
	v_cndmask_b32_e32 v218, v218, v219, vcc
	v_rsq_f32_e32 v218, v218
	s_ashr_i32 s9, s8, 31
	s_lshl_b32 s12, s48, 1
	s_ashr_i32 s13, s12, 31
	v_mul_f32_e32 v219, 0x45800000, v218
	v_cndmask_b32_e32 v230, v218, v219, vcc
	v_mul_f32_e32 v230, 0xbfb8aa3b, v230
	v_mul_f32_e32 v220, v126, v230
	v_mul_f32_e32 v231, v122, v230
	v_exp_f32_e32 v220, v220
	v_exp_f32_e32 v231, v231
	v_mul_f32_e32 v241, v123, v230
	v_add_f32_e32 v220, 1.0, v220
	v_rcp_f32_e32 v240, v220
	v_add_f32_e32 v220, 1.0, v231
	v_mul_f32_e32 v231, v127, v230
	v_exp_f32_e32 v231, v231
	v_exp_f32_e32 v243, v241
	v_rcp_f32_e32 v242, v220
	v_add_f32_e32 v220, 1.0, v231
	v_mul_f32_e32 v231, v128, v230
	v_rcp_f32_e32 v241, v220
	v_add_f32_e32 v220, 1.0, v243
	v_mul_f32_e32 v243, v124, v230
	v_exp_f32_e32 v231, v231
	v_exp_f32_e32 v245, v243
	v_rcp_f32_e32 v243, v220
	v_add_f32_e32 v220, 1.0, v231
	v_mul_f32_e32 v231, v129, v230
	v_rcp_f32_e32 v244, v220
	v_add_f32_e32 v220, 1.0, v245
	v_mul_f32_e32 v245, v125, v230
	v_exp_f32_e32 v231, v231
	v_exp_f32_e32 v247, v245
	s_lshl_b64 s[8:9], s[8:9], 22
	s_add_u32 s34, s56, s8
	s_addc_u32 s35, s57, s9
	s_lshl_b64 s[8:9], s[12:13], 14
	v_rcp_f32_e32 v246, v220
	v_add_f32_e32 v220, 1.0, v231
	s_add_u32 s43, s34, s8
	v_rcp_f32_e32 v245, v220
	v_add_f32_e32 v220, 1.0, v247
	s_addc_u32 s41, s35, s9
	s_lshl_b64 s[8:9], s[28:29], 1
	v_rcp_f32_e32 v247, v220
	s_add_u32 s8, s43, s8
	s_addc_u32 s9, s41, s9
	v_lshlrev_b32_e32 v232, 16, v190
	v_and_b32_e32 v233, 0xffff0000, v190
	v_lshlrev_b32_e32 v190, 16, v191
	v_and_b32_e32 v191, 0xffff0000, v191
	v_lshlrev_b32_e32 v234, 16, v192
	v_and_b32_e32 v235, 0xffff0000, v192
	v_lshlrev_b32_e32 v192, 16, v193
	v_and_b32_e32 v193, 0xffff0000, v193
	v_lshlrev_b32_e32 v236, 16, v186
	v_and_b32_e32 v237, 0xffff0000, v186
	v_lshlrev_b32_e32 v186, 16, v187
	v_and_b32_e32 v187, 0xffff0000, v187
	v_lshlrev_b32_e32 v238, 16, v188
	v_and_b32_e32 v239, 0xffff0000, v188
	v_lshlrev_b32_e32 v188, 16, v189
	v_and_b32_e32 v189, 0xffff0000, v189
	s_cmp_gt_i32 s72, 1
	v_lshl_add_u64 v[218:219], v[200:201], 1, s[8:9]
	v_pk_fma_f32 v[232:233], v[240:241], v[232:233], v[236:237]
	v_pk_fma_f32 v[234:235], v[242:243], v[234:235], v[238:239]
	v_pk_fma_f32 v[190:191], v[244:245], v[190:191], v[186:187]
	v_pk_fma_f32 v[192:193], v[246:247], v[192:193], v[188:189]
	s_cselect_b64 s[12:13], -1, 0
	v_lshl_add_u64 v[218:219], v[202:203], 1, v[218:219]
	v_cvt_pk_bf16_f32 v186, v232, v233
	v_cvt_pk_bf16_f32 v187, v190, v191
	s_mov_b64 s[8:9], -1
	s_and_b64 vcc, exec, s[12:13]
	v_cvt_pk_bf16_f32 v188, v234, v235
	v_cvt_pk_bf16_f32 v189, v192, v193
	s_cbranch_vccz .LBB0_1147
	global_store_dwordx2 v[218:219], v[186:187], off
	global_store_dwordx2 v[218:219], v[188:189], off offset:512
	s_mov_b64 s[8:9], 0

.LBB0_1149:
	v_mul_f32_e32 v220, v110, v230
	v_mul_f32_e32 v231, v106, v230
	v_exp_f32_e32 v220, v220
	v_exp_f32_e32 v231, v231
	v_mul_f32_e32 v233, v107, v230
	v_add_f32_e32 v220, 1.0, v220
	v_rcp_f32_e32 v232, v220
	v_add_f32_e32 v220, 1.0, v231
	v_mul_f32_e32 v231, v111, v230
	v_exp_f32_e32 v231, v231
	v_exp_f32_e32 v235, v233
	v_rcp_f32_e32 v234, v220
	v_add_f32_e32 v220, 1.0, v231
	v_mul_f32_e32 v231, v112, v230
	v_exp_f32_e32 v231, v231
	v_rcp_f32_e32 v233, v220
	v_add_f32_e32 v220, 1.0, v235
	v_mul_f32_e32 v235, v108, v230
	v_exp_f32_e32 v237, v235
	v_rcp_f32_e32 v235, v220
	v_add_f32_e32 v220, 1.0, v231
	v_mul_f32_e32 v231, v113, v230
	v_mul_f32_e32 v230, v109, v230
	v_exp_f32_e32 v231, v231
	v_exp_f32_e32 v238, v230
	v_rcp_f32_e32 v236, v220
	v_add_f32_e32 v220, 1.0, v237
	v_rcp_f32_e32 v230, v220
	v_add_f32_e32 v220, 1.0, v231
	v_rcp_f32_e32 v237, v220
	v_add_f32_e32 v220, 1.0, v238
	v_rcp_f32_e32 v231, v220
	v_lshlrev_b32_e32 v186, 16, v182
	v_and_b32_e32 v187, 0xffff0000, v182
	v_lshlrev_b32_e32 v182, 16, v183
	v_and_b32_e32 v183, 0xffff0000, v183
	v_lshlrev_b32_e32 v188, 16, v184
	v_and_b32_e32 v189, 0xffff0000, v184
	v_lshlrev_b32_e32 v184, 16, v185
	v_and_b32_e32 v185, 0xffff0000, v185
	v_lshlrev_b32_e32 v190, 16, v178
	v_and_b32_e32 v191, 0xffff0000, v178
	v_lshlrev_b32_e32 v178, 16, v179
	v_and_b32_e32 v179, 0xffff0000, v179
	v_lshlrev_b32_e32 v192, 16, v180
	v_and_b32_e32 v193, 0xffff0000, v180
	v_lshlrev_b32_e32 v180, 16, v181
	v_and_b32_e32 v181, 0xffff0000, v181
	v_pk_fma_f32 v[186:187], v[232:233], v[186:187], v[190:191]
	v_pk_fma_f32 v[188:189], v[234:235], v[188:189], v[192:193]
	v_pk_fma_f32 v[182:183], v[236:237], v[182:183], v[178:179]
	v_pk_fma_f32 v[184:185], v[230:231], v[184:185], v[180:181]
	v_cndmask_b32_e64 v178, 0, 1, s[12:13]
	s_mov_b64 s[34:35], -1
	v_cmp_ne_u32_e64 s[8:9], 1, v178
	s_andn2_b64 vcc, exec, s[12:13]
	v_cvt_pk_bf16_f32 v178, v186, v187
	v_cvt_pk_bf16_f32 v179, v182, v183
	v_cvt_pk_bf16_f32 v180, v188, v189
	v_cvt_pk_bf16_f32 v181, v184, v185
	s_cbranch_vccnz .LBB0_1151
	v_add_co_u32_e32 v182, vcc, 0x800000, v218
	s_mov_b64 s[34:35], 0
	s_nop 0
	v_addc_co_u32_e32 v183, vcc, 0, v219, vcc
	global_store_dwordx2 v[182:183], v[178:179], off
	global_store_dwordx2 v[182:183], v[180:181], off offset:512

.LBB0_1153:
	s_nop 1
	v_fmamk_f32 v178, v229, 0x3a800000, v228
	v_mul_f32_e32 v179, 0x4b800000, v178
	v_cmp_gt_f32_e32 vcc, s69, v178
	s_lshl_b64 s[12:13], s[30:31], 1
	s_add_u32 s12, s43, s12
	v_cndmask_b32_e32 v178, v178, v179, vcc
	v_rsq_f32_e32 v178, v178
	s_addc_u32 s13, s41, s13
	v_lshlrev_b32_e32 v182, 16, v174
	v_and_b32_e32 v183, 0xffff0000, v174
	v_mul_f32_e32 v179, 0x45800000, v178
	v_cndmask_b32_e32 v180, v178, v179, vcc
	v_mul_f32_e32 v180, 0xbfb8aa3b, v180
	v_mul_f32_e32 v181, v118, v180
	v_mul_f32_e32 v190, v114, v180
	v_exp_f32_e32 v181, v181
	v_exp_f32_e32 v191, v190
	v_mul_f32_e32 v192, v115, v180
	v_add_f32_e32 v181, 1.0, v181
	v_rcp_f32_e32 v190, v181
	v_add_f32_e32 v181, 1.0, v191
	v_mul_f32_e32 v191, v119, v180
	v_exp_f32_e32 v191, v191
	v_exp_f32_e32 v193, v192
	v_rcp_f32_e32 v192, v181
	v_add_f32_e32 v181, 1.0, v191
	v_rcp_f32_e32 v191, v181
	v_add_f32_e32 v181, 1.0, v193
	v_mul_f32_e32 v193, v120, v180
	v_exp_f32_e32 v220, v193
	v_mul_f32_e32 v193, v116, v180
	v_exp_f32_e32 v229, v193
	v_rcp_f32_e32 v193, v181
	v_add_f32_e32 v181, 1.0, v220
	v_mul_f32_e32 v220, v121, v180
	v_rcp_f32_e32 v230, v181
	v_add_f32_e32 v181, 1.0, v229
	v_mul_f32_e32 v229, v117, v180
	v_exp_f32_e32 v220, v220
	v_exp_f32_e32 v229, v229
	v_rcp_f32_e32 v232, v181
	v_add_f32_e32 v181, 1.0, v220
	v_rcp_f32_e32 v231, v181
	v_add_f32_e32 v181, 1.0, v229
	v_rcp_f32_e32 v233, v181
	v_lshlrev_b32_e32 v174, 16, v175
	v_and_b32_e32 v175, 0xffff0000, v175
	v_lshlrev_b32_e32 v184, 16, v176
	v_and_b32_e32 v185, 0xffff0000, v176
	v_lshlrev_b32_e32 v176, 16, v177
	v_and_b32_e32 v177, 0xffff0000, v177
	v_lshlrev_b32_e32 v186, 16, v170
	v_and_b32_e32 v187, 0xffff0000, v170
	v_lshlrev_b32_e32 v170, 16, v171
	v_and_b32_e32 v171, 0xffff0000, v171
	v_lshlrev_b32_e32 v188, 16, v172
	v_and_b32_e32 v189, 0xffff0000, v172
	v_lshlrev_b32_e32 v172, 16, v173
	v_and_b32_e32 v173, 0xffff0000, v173
	v_lshl_add_u64 v[178:179], v[200:201], 1, s[12:13]
	v_pk_fma_f32 v[182:183], v[190:191], v[182:183], v[186:187]
	v_pk_fma_f32 v[184:185], v[192:193], v[184:185], v[188:189]
	v_pk_fma_f32 v[174:175], v[230:231], v[174:175], v[170:171]
	v_pk_fma_f32 v[176:177], v[232:233], v[176:177], v[172:173]
	v_lshl_add_u64 v[178:179], v[202:203], 1, v[178:179]
	v_cvt_pk_bf16_f32 v170, v182, v183
	v_cvt_pk_bf16_f32 v171, v174, v175
	s_mov_b64 s[12:13], -1
	s_and_b64 vcc, exec, s[8:9]
	v_cvt_pk_bf16_f32 v172, v184, v185
	v_cvt_pk_bf16_f32 v173, v176, v177
	s_cbranch_vccnz .LBB0_1155
	s_mov_b64 s[12:13], 0
	global_store_dwordx2 v[178:179], v[170:171], off
	global_store_dwordx2 v[178:179], v[172:173], off offset:512

.LBB0_1157:
	v_mul_f32_e32 v181, v94, v180
	v_mul_f32_e32 v182, v90, v180
	v_exp_f32_e32 v181, v181
	v_exp_f32_e32 v183, v182
	v_mul_f32_e32 v184, v91, v180
	v_add_f32_e32 v181, 1.0, v181
	v_rcp_f32_e32 v182, v181
	v_add_f32_e32 v181, 1.0, v183
	v_mul_f32_e32 v183, v95, v180
	v_exp_f32_e32 v183, v183
	v_exp_f32_e32 v185, v184
	v_rcp_f32_e32 v184, v181
	v_add_f32_e32 v181, 1.0, v183
	v_rcp_f32_e32 v183, v181
	v_add_f32_e32 v181, 1.0, v185
	v_mul_f32_e32 v185, v96, v180
	v_exp_f32_e32 v186, v185
	v_mul_f32_e32 v185, v92, v180
	v_exp_f32_e32 v187, v185
	v_rcp_f32_e32 v185, v181
	v_add_f32_e32 v181, 1.0, v186
	v_rcp_f32_e32 v186, v181
	v_add_f32_e32 v181, 1.0, v187
	v_mul_f32_e32 v187, v97, v180
	v_mul_f32_e32 v180, v93, v180
	v_exp_f32_e32 v187, v187
	v_exp_f32_e32 v188, v180
	v_rcp_f32_e32 v180, v181
	v_add_f32_e32 v181, 1.0, v187
	v_rcp_f32_e32 v187, v181
	v_add_f32_e32 v181, 1.0, v188
	v_rcp_f32_e32 v181, v181
	v_lshlrev_b32_e32 v170, 16, v166
	v_and_b32_e32 v171, 0xffff0000, v166
	v_lshlrev_b32_e32 v166, 16, v167
	v_and_b32_e32 v167, 0xffff0000, v167
	v_lshlrev_b32_e32 v172, 16, v168
	v_and_b32_e32 v173, 0xffff0000, v168
	v_lshlrev_b32_e32 v168, 16, v169
	v_and_b32_e32 v169, 0xffff0000, v169
	v_lshlrev_b32_e32 v174, 16, v162
	v_and_b32_e32 v175, 0xffff0000, v162
	v_lshlrev_b32_e32 v162, 16, v163
	v_and_b32_e32 v163, 0xffff0000, v163
	v_lshlrev_b32_e32 v176, 16, v164
	v_and_b32_e32 v177, 0xffff0000, v164
	v_lshlrev_b32_e32 v164, 16, v165
	v_and_b32_e32 v165, 0xffff0000, v165
	v_pk_fma_f32 v[170:171], v[182:183], v[170:171], v[174:175]
	v_pk_fma_f32 v[172:173], v[184:185], v[172:173], v[176:177]
	v_pk_fma_f32 v[166:167], v[186:187], v[166:167], v[162:163]
	v_pk_fma_f32 v[168:169], v[180:181], v[168:169], v[164:165]
	s_mov_b64 s[12:13], -1
	s_and_b64 vcc, exec, s[8:9]
	v_cvt_pk_bf16_f32 v162, v170, v171
	v_cvt_pk_bf16_f32 v163, v166, v167
	v_cvt_pk_bf16_f32 v164, v172, v173
	v_cvt_pk_bf16_f32 v165, v168, v169
	s_cbranch_vccnz .LBB0_1159
	v_add_co_u32_e32 v166, vcc, 0x800000, v178
	s_mov_b64 s[12:13], 0
	s_nop 0
	v_addc_co_u32_e32 v167, vcc, 0, v179, vcc
	global_store_dwordx2 v[166:167], v[162:163], off
	global_store_dwordx2 v[166:167], v[164:165], off offset:512

.LBB0_1161:
	s_nop 1
	v_fmamk_f32 v162, v207, 0x3a800000, v228
	v_mul_f32_e32 v163, 0x4b800000, v162
	v_cmp_gt_f32_e32 vcc, s69, v162
	v_lshlrev_b32_e32 v166, 16, v158
	v_and_b32_e32 v167, 0xffff0000, v158
	v_cndmask_b32_e32 v162, v162, v163, vcc
	v_rsq_f32_e32 v164, v162
	v_lshlrev_b32_e32 v158, 16, v159
	v_and_b32_e32 v159, 0xffff0000, v159
	v_lshlrev_b32_e32 v168, 16, v160
	v_mul_f32_e32 v165, 0x45800000, v164
	v_cndmask_b32_e32 v164, v164, v165, vcc
	v_mul_f32_e32 v164, 0xbfb8aa3b, v164
	v_mul_f32_e32 v165, v102, v164
	v_mul_f32_e32 v174, v98, v164
	v_exp_f32_e32 v165, v165
	v_exp_f32_e32 v175, v174
	v_mul_f32_e32 v176, v99, v164
	v_add_f32_e32 v165, 1.0, v165
	v_rcp_f32_e32 v174, v165
	v_add_f32_e32 v165, 1.0, v175
	v_mul_f32_e32 v175, v103, v164
	v_exp_f32_e32 v175, v175
	v_exp_f32_e32 v177, v176
	v_rcp_f32_e32 v176, v165
	v_add_f32_e32 v165, 1.0, v175
	v_rcp_f32_e32 v175, v165
	v_add_f32_e32 v165, 1.0, v177
	v_mul_f32_e32 v177, v104, v164
	v_exp_f32_e32 v178, v177
	v_mul_f32_e32 v177, v100, v164
	v_exp_f32_e32 v179, v177
	v_rcp_f32_e32 v177, v165
	v_add_f32_e32 v165, 1.0, v178
	v_rcp_f32_e32 v178, v165
	v_add_f32_e32 v165, 1.0, v179
	v_mul_f32_e32 v179, v105, v164
	v_mul_f32_e32 v180, v101, v164
	v_exp_f32_e32 v179, v179
	v_exp_f32_e32 v181, v180
	v_rcp_f32_e32 v180, v165
	v_add_f32_e32 v165, 1.0, v179
	v_rcp_f32_e32 v179, v165
	v_add_f32_e32 v165, 1.0, v181
	v_rcp_f32_e32 v181, v165
	v_and_b32_e32 v169, 0xffff0000, v160
	v_lshlrev_b32_e32 v160, 16, v161
	v_and_b32_e32 v161, 0xffff0000, v161
	v_lshlrev_b32_e32 v170, 16, v154
	v_and_b32_e32 v171, 0xffff0000, v154
	v_lshlrev_b32_e32 v154, 16, v155
	v_and_b32_e32 v155, 0xffff0000, v155
	v_lshlrev_b32_e32 v172, 16, v156
	v_and_b32_e32 v173, 0xffff0000, v156
	v_lshlrev_b32_e32 v156, 16, v157
	v_and_b32_e32 v157, 0xffff0000, v157
	v_pk_fma_f32 v[166:167], v[174:175], v[166:167], v[170:171]
	v_pk_fma_f32 v[168:169], v[176:177], v[168:169], v[172:173]
	v_pk_fma_f32 v[158:159], v[178:179], v[158:159], v[154:155]
	v_pk_fma_f32 v[160:161], v[180:181], v[160:161], v[156:157]
	v_lshl_add_u64 v[162:163], v[218:219], 0, s[38:39]
	v_cvt_pk_bf16_f32 v154, v166, v167
	v_cvt_pk_bf16_f32 v155, v158, v159
	s_mov_b64 s[12:13], -1
	s_and_b64 vcc, exec, s[8:9]
	v_cvt_pk_bf16_f32 v156, v168, v169
	v_cvt_pk_bf16_f32 v157, v160, v161
	s_cbranch_vccnz .LBB0_1163
	s_mov_b64 s[12:13], 0
	global_store_dwordx2 v[162:163], v[154:155], off
	global_store_dwordx2 v[162:163], v[156:157], off offset:512

.LBB0_1165:
	v_mul_f32_e32 v165, v78, v164
	v_mul_f32_e32 v166, v74, v164
	v_exp_f32_e32 v165, v165
	v_exp_f32_e32 v167, v166
	v_mul_f32_e32 v168, v75, v164
	v_add_f32_e32 v165, 1.0, v165
	v_rcp_f32_e32 v166, v165
	v_add_f32_e32 v165, 1.0, v167
	v_mul_f32_e32 v167, v79, v164
	v_exp_f32_e32 v167, v167
	v_exp_f32_e32 v169, v168
	v_rcp_f32_e32 v168, v165
	v_add_f32_e32 v165, 1.0, v167
	v_rcp_f32_e32 v167, v165
	v_add_f32_e32 v165, 1.0, v169
	v_mul_f32_e32 v169, v80, v164
	v_exp_f32_e32 v170, v169
	v_mul_f32_e32 v169, v76, v164
	v_exp_f32_e32 v171, v169
	v_rcp_f32_e32 v169, v165
	v_add_f32_e32 v165, 1.0, v170
	v_rcp_f32_e32 v170, v165
	v_add_f32_e32 v165, 1.0, v171
	v_mul_f32_e32 v171, v81, v164
	v_mul_f32_e32 v164, v77, v164
	v_exp_f32_e32 v171, v171
	v_exp_f32_e32 v172, v164
	v_rcp_f32_e32 v164, v165
	v_add_f32_e32 v165, 1.0, v171
	v_rcp_f32_e32 v171, v165
	v_add_f32_e32 v165, 1.0, v172
	v_rcp_f32_e32 v165, v165
	v_lshlrev_b32_e32 v154, 16, v150
	v_and_b32_e32 v155, 0xffff0000, v150
	v_lshlrev_b32_e32 v150, 16, v151
	v_and_b32_e32 v151, 0xffff0000, v151
	v_lshlrev_b32_e32 v156, 16, v152
	v_and_b32_e32 v157, 0xffff0000, v152
	v_lshlrev_b32_e32 v152, 16, v153
	v_and_b32_e32 v153, 0xffff0000, v153
	v_lshlrev_b32_e32 v158, 16, v146
	v_and_b32_e32 v159, 0xffff0000, v146
	v_lshlrev_b32_e32 v146, 16, v147
	v_and_b32_e32 v147, 0xffff0000, v147
	v_lshlrev_b32_e32 v160, 16, v148
	v_and_b32_e32 v161, 0xffff0000, v148
	v_lshlrev_b32_e32 v148, 16, v149
	v_and_b32_e32 v149, 0xffff0000, v149
	v_pk_fma_f32 v[154:155], v[166:167], v[154:155], v[158:159]
	v_pk_fma_f32 v[156:157], v[168:169], v[156:157], v[160:161]
	v_pk_fma_f32 v[150:151], v[170:171], v[150:151], v[146:147]
	v_pk_fma_f32 v[152:153], v[164:165], v[152:153], v[148:149]
	s_mov_b64 s[12:13], -1
	s_and_b64 vcc, exec, s[8:9]
	v_cvt_pk_bf16_f32 v146, v154, v155
	v_cvt_pk_bf16_f32 v147, v150, v151
	v_cvt_pk_bf16_f32 v148, v156, v157
	v_cvt_pk_bf16_f32 v149, v152, v153
	s_cbranch_vccnz .LBB0_1167
	v_add_co_u32_e32 v150, vcc, 0x800000, v162
	s_mov_b64 s[12:13], 0
	s_nop 0
	v_addc_co_u32_e32 v151, vcc, 0, v163, vcc
	global_store_dwordx2 v[150:151], v[146:147], off
	global_store_dwordx2 v[150:151], v[148:149], off offset:512

.LBB0_1169:
	s_nop 1
	v_fmamk_f32 v146, v205, 0x3a800000, v228
	v_mul_f32_e32 v147, 0x4b800000, v146
	v_cmp_gt_f32_e32 vcc, s69, v146
	s_lshl_b64 s[12:13], s[36:37], 1
	s_add_u32 s12, s43, s12
	v_cndmask_b32_e32 v146, v146, v147, vcc
	v_rsq_f32_e32 v146, v146
	s_addc_u32 s13, s41, s13
	v_lshlrev_b32_e32 v150, 16, v142
	v_and_b32_e32 v151, 0xffff0000, v142
	v_mul_f32_e32 v147, 0x45800000, v146
	v_cndmask_b32_e32 v148, v146, v147, vcc
	v_mul_f32_e32 v148, 0xbfb8aa3b, v148
	v_mul_f32_e32 v149, v86, v148
	v_mul_f32_e32 v158, v82, v148
	v_exp_f32_e32 v149, v149
	v_exp_f32_e32 v159, v158
	v_mul_f32_e32 v160, v83, v148
	v_add_f32_e32 v149, 1.0, v149
	v_rcp_f32_e32 v158, v149
	v_add_f32_e32 v149, 1.0, v159
	v_mul_f32_e32 v159, v87, v148
	v_exp_f32_e32 v159, v159
	v_exp_f32_e32 v161, v160
	v_rcp_f32_e32 v160, v149
	v_add_f32_e32 v149, 1.0, v159
	v_rcp_f32_e32 v159, v149
	v_add_f32_e32 v149, 1.0, v161
	v_mul_f32_e32 v161, v88, v148
	v_exp_f32_e32 v162, v161
	v_mul_f32_e32 v161, v84, v148
	v_exp_f32_e32 v163, v161
	v_rcp_f32_e32 v161, v149
	v_add_f32_e32 v149, 1.0, v162
	v_rcp_f32_e32 v162, v149
	v_add_f32_e32 v149, 1.0, v163
	v_mul_f32_e32 v163, v89, v148
	v_mul_f32_e32 v164, v85, v148
	v_exp_f32_e32 v163, v163
	v_exp_f32_e32 v165, v164
	v_rcp_f32_e32 v164, v149
	v_add_f32_e32 v149, 1.0, v163
	v_rcp_f32_e32 v163, v149
	v_add_f32_e32 v149, 1.0, v165
	v_rcp_f32_e32 v165, v149
	v_lshlrev_b32_e32 v142, 16, v143
	v_and_b32_e32 v143, 0xffff0000, v143
	v_lshlrev_b32_e32 v152, 16, v144
	v_and_b32_e32 v153, 0xffff0000, v144
	v_lshlrev_b32_e32 v144, 16, v145
	v_and_b32_e32 v145, 0xffff0000, v145
	v_lshlrev_b32_e32 v154, 16, v138
	v_and_b32_e32 v155, 0xffff0000, v138
	v_lshlrev_b32_e32 v138, 16, v139
	v_and_b32_e32 v139, 0xffff0000, v139
	v_lshlrev_b32_e32 v156, 16, v140
	v_and_b32_e32 v157, 0xffff0000, v140
	v_lshlrev_b32_e32 v140, 16, v141
	v_and_b32_e32 v141, 0xffff0000, v141
	v_lshl_add_u64 v[146:147], v[200:201], 1, s[12:13]
	v_pk_fma_f32 v[150:151], v[158:159], v[150:151], v[154:155]
	v_pk_fma_f32 v[152:153], v[160:161], v[152:153], v[156:157]
	v_pk_fma_f32 v[142:143], v[162:163], v[142:143], v[138:139]
	v_pk_fma_f32 v[144:145], v[164:165], v[144:145], v[140:141]
	v_lshl_add_u64 v[146:147], v[202:203], 1, v[146:147]
	v_cvt_pk_bf16_f32 v138, v150, v151
	v_cvt_pk_bf16_f32 v139, v142, v143
	s_mov_b64 s[12:13], -1
	s_and_b64 vcc, exec, s[8:9]
	v_cvt_pk_bf16_f32 v140, v152, v153
	v_cvt_pk_bf16_f32 v141, v144, v145
	s_cbranch_vccnz .LBB0_1171
	s_mov_b64 s[12:13], 0
	global_store_dwordx2 v[146:147], v[138:139], off
	global_store_dwordx2 v[146:147], v[140:141], off offset:512

.LBB0_1173:
	v_mul_f32_e32 v149, v70, v148
	v_mul_f32_e32 v150, v66, v148
	v_exp_f32_e32 v149, v149
	v_exp_f32_e32 v151, v150
	v_mul_f32_e32 v152, v67, v148
	v_add_f32_e32 v149, 1.0, v149
	v_rcp_f32_e32 v150, v149
	v_add_f32_e32 v149, 1.0, v151
	v_mul_f32_e32 v151, v71, v148
	v_exp_f32_e32 v151, v151
	v_exp_f32_e32 v153, v152
	v_rcp_f32_e32 v152, v149
	v_add_f32_e32 v149, 1.0, v151
	v_rcp_f32_e32 v151, v149
	v_add_f32_e32 v149, 1.0, v153
	v_mul_f32_e32 v153, v72, v148
	v_exp_f32_e32 v154, v153
	v_mul_f32_e32 v153, v68, v148
	v_exp_f32_e32 v155, v153
	v_rcp_f32_e32 v153, v149
	v_add_f32_e32 v149, 1.0, v154
	v_rcp_f32_e32 v154, v149
	v_add_f32_e32 v149, 1.0, v155
	v_mul_f32_e32 v155, v73, v148
	v_mul_f32_e32 v148, v69, v148
	v_exp_f32_e32 v155, v155
	v_exp_f32_e32 v156, v148
	v_rcp_f32_e32 v148, v149
	v_add_f32_e32 v149, 1.0, v155
	v_rcp_f32_e32 v155, v149
	v_add_f32_e32 v149, 1.0, v156
	v_rcp_f32_e32 v149, v149
	v_lshlrev_b32_e32 v138, 16, v134
	v_and_b32_e32 v139, 0xffff0000, v134
	v_lshlrev_b32_e32 v134, 16, v135
	v_and_b32_e32 v135, 0xffff0000, v135
	v_lshlrev_b32_e32 v140, 16, v136
	v_and_b32_e32 v141, 0xffff0000, v136
	v_lshlrev_b32_e32 v136, 16, v137
	v_and_b32_e32 v137, 0xffff0000, v137
	v_lshlrev_b32_e32 v142, 16, v130
	v_and_b32_e32 v143, 0xffff0000, v130
	v_lshlrev_b32_e32 v130, 16, v131
	v_and_b32_e32 v131, 0xffff0000, v131
	v_lshlrev_b32_e32 v144, 16, v132
	v_and_b32_e32 v145, 0xffff0000, v132
	v_lshlrev_b32_e32 v132, 16, v133
	v_and_b32_e32 v133, 0xffff0000, v133
	v_pk_fma_f32 v[138:139], v[150:151], v[138:139], v[142:143]
	v_pk_fma_f32 v[140:141], v[152:153], v[140:141], v[144:145]
	v_pk_fma_f32 v[134:135], v[154:155], v[134:135], v[130:131]
	v_pk_fma_f32 v[136:137], v[148:149], v[136:137], v[132:133]
	s_mov_b64 s[12:13], -1
	s_and_b64 vcc, exec, s[8:9]
	v_cvt_pk_bf16_f32 v130, v138, v139
	v_cvt_pk_bf16_f32 v131, v134, v135
	v_cvt_pk_bf16_f32 v132, v140, v141
	v_cvt_pk_bf16_f32 v133, v136, v137
	s_cbranch_vccnz .LBB0_1175
	v_add_co_u32_e32 v134, vcc, 0x800000, v146
	s_mov_b64 s[12:13], 0
	s_nop 0
	v_addc_co_u32_e32 v135, vcc, 0, v147, vcc
	global_store_dwordx2 v[134:135], v[130:131], off
	global_store_dwordx2 v[134:135], v[132:133], off offset:512

.LBB0_1197:
	s_waitcnt vmcnt(0)
	v_fmamk_f32 v142, v142, 0x3a800000, v228
	v_mul_f32_e32 v143, 0x4b800000, v142
	v_cmp_gt_f32_e32 vcc, s69, v142
	s_lshl_b32 s8, s50, 2
	s_or_b32 s8, s8, s64
	v_cndmask_b32_e32 v142, v142, v143, vcc
	v_rsq_f32_e32 v142, v142
	s_lshl_b32 s12, s48, 1
	s_ashr_i32 s9, s8, 31
	s_or_b32 s12, s12, 1
	v_mul_f32_e32 v143, 0x45800000, v142
	v_cndmask_b32_e32 v151, v142, v143, vcc
	v_mul_f32_e32 v151, 0xbfb8aa3b, v151
	v_mul_f32_e32 v162, v63, v151
	v_mul_f32_e32 v161, v58, v151
	v_exp_f32_e32 v163, v162
	v_mul_f32_e32 v162, v59, v151
	v_exp_f32_e32 v161, v161
	v_exp_f32_e32 v164, v162
	v_mul_f32_e32 v166, v65, v151
	v_add_f32_e32 v161, 1.0, v161
	v_mul_f32_e32 v165, v60, v151
	v_mul_f32_e32 v160, v62, v151
	v_rcp_f32_e32 v162, v161
	v_add_f32_e32 v161, 1.0, v163
	v_add_f32_e32 v163, 1.0, v164
	v_mul_f32_e32 v164, v64, v151
	v_exp_f32_e32 v167, v166
	v_mul_f32_e32 v166, v61, v151
	v_exp_f32_e32 v165, v165
	v_exp_f32_e32 v160, v160
	v_exp_f32_e32 v164, v164
	v_exp_f32_e32 v168, v166
	s_ashr_i32 s13, s12, 31
	s_lshl_b64 s[8:9], s[8:9], 22
	s_add_u32 s34, s56, s8
	v_add_f32_e32 v165, 1.0, v165
	s_addc_u32 s35, s57, s9
	s_lshl_b64 s[8:9], s[12:13], 14
	v_add_f32_e32 v160, 1.0, v160
	v_add_f32_e32 v164, 1.0, v164
	v_rcp_f32_e32 v166, v165
	v_add_f32_e32 v165, 1.0, v167
	v_add_f32_e32 v167, 1.0, v168
	s_add_u32 s43, s34, s8
	v_rcp_f32_e32 v160, v160
	v_rcp_f32_e32 v161, v161
	v_rcp_f32_e32 v163, v163
	v_rcp_f32_e32 v164, v164
	v_rcp_f32_e32 v165, v165
	v_rcp_f32_e32 v167, v167
	s_addc_u32 s41, s35, s9
	s_lshl_b64 s[8:9], s[28:29], 1
	s_add_u32 s8, s43, s8
	s_addc_u32 s9, s41, s9
	v_lshlrev_b32_e32 v152, 16, v126
	v_and_b32_e32 v153, 0xffff0000, v126
	v_lshlrev_b32_e32 v126, 16, v127
	v_and_b32_e32 v127, 0xffff0000, v127
	v_lshlrev_b32_e32 v154, 16, v128
	v_and_b32_e32 v155, 0xffff0000, v128
	v_lshlrev_b32_e32 v128, 16, v129
	v_and_b32_e32 v129, 0xffff0000, v129
	v_lshlrev_b32_e32 v156, 16, v122
	v_and_b32_e32 v157, 0xffff0000, v122
	v_lshlrev_b32_e32 v122, 16, v123
	v_and_b32_e32 v123, 0xffff0000, v123
	v_lshlrev_b32_e32 v158, 16, v124
	v_and_b32_e32 v159, 0xffff0000, v124
	v_lshlrev_b32_e32 v124, 16, v125
	v_and_b32_e32 v125, 0xffff0000, v125
	v_lshl_add_u64 v[142:143], v[200:201], 1, s[8:9]
	v_pk_fma_f32 v[152:153], v[160:161], v[152:153], v[156:157]
	v_pk_fma_f32 v[154:155], v[162:163], v[154:155], v[158:159]
	v_pk_fma_f32 v[126:127], v[164:165], v[126:127], v[122:123]
	v_pk_fma_f32 v[128:129], v[166:167], v[128:129], v[124:125]
	s_cmp_gt_i32 s72, 1
	v_lshl_add_u64 v[142:143], v[202:203], 1, v[142:143]
	s_cselect_b64 s[12:13], -1, 0
	s_cmp_lt_i32 s72, 2
	v_cvt_pk_bf16_f32 v122, v152, v153
	v_cvt_pk_bf16_f32 v123, v126, v127
	s_mov_b64 s[8:9], -1
	v_cvt_pk_bf16_f32 v124, v154, v155
	v_cvt_pk_bf16_f32 v125, v128, v129
	s_cbranch_scc1 .LBB0_1199
	s_mov_b64 s[8:9], 0
	global_store_dwordx2 v[142:143], v[122:123], off
	global_store_dwordx2 v[142:143], v[124:125], off offset:512

.LBB0_1201:
	v_mul_f32_e32 v152, v47, v151
	v_mul_f32_e32 v147, v42, v151
	v_exp_f32_e32 v153, v152
	v_mul_f32_e32 v152, v43, v151
	v_exp_f32_e32 v147, v147
	v_exp_f32_e32 v154, v152
	v_mul_f32_e32 v155, v44, v151
	v_add_f32_e32 v147, 1.0, v147
	v_mul_f32_e32 v146, v46, v151
	v_rcp_f32_e32 v152, v147
	v_add_f32_e32 v147, 1.0, v153
	v_add_f32_e32 v153, 1.0, v154
	v_mul_f32_e32 v154, v48, v151
	v_mul_f32_e32 v156, v49, v151
	v_mul_f32_e32 v151, v45, v151
	v_exp_f32_e32 v155, v155
	v_exp_f32_e32 v146, v146
	v_exp_f32_e32 v154, v154
	v_exp_f32_e32 v157, v156
	v_exp_f32_e32 v151, v151
	v_add_f32_e32 v155, 1.0, v155
	v_add_f32_e32 v146, 1.0, v146
	v_add_f32_e32 v154, 1.0, v154
	v_rcp_f32_e32 v156, v155
	v_add_f32_e32 v155, 1.0, v157
	v_add_f32_e32 v151, 1.0, v151
	v_rcp_f32_e32 v146, v146
	v_rcp_f32_e32 v147, v147
	v_rcp_f32_e32 v153, v153
	v_rcp_f32_e32 v154, v154
	v_rcp_f32_e32 v155, v155
	v_rcp_f32_e32 v157, v151
	v_lshlrev_b32_e32 v122, 16, v118
	v_and_b32_e32 v123, 0xffff0000, v118
	v_lshlrev_b32_e32 v118, 16, v119
	v_and_b32_e32 v119, 0xffff0000, v119
	v_lshlrev_b32_e32 v124, 16, v120
	v_and_b32_e32 v125, 0xffff0000, v120
	v_lshlrev_b32_e32 v120, 16, v121
	v_and_b32_e32 v121, 0xffff0000, v121
	v_lshlrev_b32_e32 v126, 16, v114
	v_and_b32_e32 v127, 0xffff0000, v114
	v_lshlrev_b32_e32 v114, 16, v115
	v_and_b32_e32 v115, 0xffff0000, v115
	v_lshlrev_b32_e32 v128, 16, v116
	v_and_b32_e32 v129, 0xffff0000, v116
	v_lshlrev_b32_e32 v116, 16, v117
	v_and_b32_e32 v117, 0xffff0000, v117
	v_pk_fma_f32 v[122:123], v[146:147], v[122:123], v[126:127]
	v_pk_fma_f32 v[124:125], v[152:153], v[124:125], v[128:129]
	v_pk_fma_f32 v[118:119], v[154:155], v[118:119], v[114:115]
	v_pk_fma_f32 v[120:121], v[156:157], v[120:121], v[116:117]
	v_cndmask_b32_e64 v114, 0, 1, s[12:13]
	s_mov_b64 s[34:35], -1
	v_cmp_ne_u32_e64 s[8:9], 1, v114
	s_andn2_b64 vcc, exec, s[12:13]
	v_cvt_pk_bf16_f32 v114, v122, v123
	v_cvt_pk_bf16_f32 v115, v118, v119
	v_cvt_pk_bf16_f32 v116, v124, v125
	v_cvt_pk_bf16_f32 v117, v120, v121
	s_cbranch_vccnz .LBB0_1203
	v_add_co_u32_e32 v118, vcc, 0x800000, v142
	s_mov_b64 s[34:35], 0
	s_nop 0
	v_addc_co_u32_e32 v119, vcc, 0, v143, vcc
	global_store_dwordx2 v[118:119], v[114:115], off
	global_store_dwordx2 v[118:119], v[116:117], off offset:512

.LBB0_1205:
	s_nop 1
	v_fmamk_f32 v114, v150, 0x3a800000, v228
	v_mul_f32_e32 v115, 0x4b800000, v114
	v_cmp_gt_f32_e32 vcc, s69, v114
	s_lshl_b64 s[12:13], s[30:31], 1
	s_add_u32 s12, s43, s12
	v_cndmask_b32_e32 v114, v114, v115, vcc
	v_rsq_f32_e32 v114, v114
	s_addc_u32 s13, s41, s13
	v_lshlrev_b32_e32 v118, 16, v110
	v_and_b32_e32 v119, 0xffff0000, v110
	v_mul_f32_e32 v115, 0x45800000, v114
	v_cndmask_b32_e32 v116, v114, v115, vcc
	v_mul_f32_e32 v116, 0xbfb8aa3b, v116
	v_mul_f32_e32 v117, v54, v116
	v_mul_f32_e32 v126, v50, v116
	v_exp_f32_e32 v117, v117
	v_exp_f32_e32 v127, v126
	v_mul_f32_e32 v128, v51, v116
	v_add_f32_e32 v117, 1.0, v117
	v_rcp_f32_e32 v126, v117
	v_add_f32_e32 v117, 1.0, v127
	v_mul_f32_e32 v127, v55, v116
	v_exp_f32_e32 v127, v127
	v_exp_f32_e32 v129, v128
	v_rcp_f32_e32 v128, v117
	v_add_f32_e32 v117, 1.0, v127
	v_rcp_f32_e32 v127, v117
	v_add_f32_e32 v117, 1.0, v129
	v_mul_f32_e32 v129, v56, v116
	v_exp_f32_e32 v144, v129
	v_mul_f32_e32 v129, v52, v116
	v_exp_f32_e32 v145, v129
	v_rcp_f32_e32 v129, v117
	v_add_f32_e32 v117, 1.0, v144
	v_rcp_f32_e32 v144, v117
	v_add_f32_e32 v117, 1.0, v145
	v_mul_f32_e32 v145, v57, v116
	v_mul_f32_e32 v146, v53, v116
	v_exp_f32_e32 v145, v145
	v_exp_f32_e32 v147, v146
	v_rcp_f32_e32 v146, v117
	v_add_f32_e32 v117, 1.0, v145
	v_rcp_f32_e32 v145, v117
	v_add_f32_e32 v117, 1.0, v147
	v_rcp_f32_e32 v147, v117
	v_lshlrev_b32_e32 v110, 16, v111
	v_and_b32_e32 v111, 0xffff0000, v111
	v_lshlrev_b32_e32 v120, 16, v112
	v_and_b32_e32 v121, 0xffff0000, v112
	v_lshlrev_b32_e32 v112, 16, v113
	v_and_b32_e32 v113, 0xffff0000, v113
	v_lshlrev_b32_e32 v122, 16, v106
	v_and_b32_e32 v123, 0xffff0000, v106
	v_lshlrev_b32_e32 v106, 16, v107
	v_and_b32_e32 v107, 0xffff0000, v107
	v_lshlrev_b32_e32 v124, 16, v108
	v_and_b32_e32 v125, 0xffff0000, v108
	v_lshlrev_b32_e32 v108, 16, v109
	v_and_b32_e32 v109, 0xffff0000, v109
	v_lshl_add_u64 v[114:115], v[200:201], 1, s[12:13]
	v_pk_fma_f32 v[118:119], v[126:127], v[118:119], v[122:123]
	v_pk_fma_f32 v[120:121], v[128:129], v[120:121], v[124:125]
	v_pk_fma_f32 v[110:111], v[144:145], v[110:111], v[106:107]
	v_pk_fma_f32 v[112:113], v[146:147], v[112:113], v[108:109]
	v_lshl_add_u64 v[114:115], v[202:203], 1, v[114:115]
	v_cvt_pk_bf16_f32 v106, v118, v119
	v_cvt_pk_bf16_f32 v107, v110, v111
	s_mov_b64 s[12:13], -1
	s_and_b64 vcc, exec, s[8:9]
	v_cvt_pk_bf16_f32 v108, v120, v121
	v_cvt_pk_bf16_f32 v109, v112, v113
	s_cbranch_vccnz .LBB0_1207
	s_mov_b64 s[12:13], 0
	global_store_dwordx2 v[114:115], v[106:107], off
	global_store_dwordx2 v[114:115], v[108:109], off offset:512

.LBB0_1209:
	v_mul_f32_e32 v117, v30, v116
	v_mul_f32_e32 v118, v26, v116
	v_exp_f32_e32 v117, v117
	v_exp_f32_e32 v119, v118
	v_mul_f32_e32 v120, v27, v116
	v_add_f32_e32 v117, 1.0, v117
	v_rcp_f32_e32 v118, v117
	v_add_f32_e32 v117, 1.0, v119
	v_mul_f32_e32 v119, v31, v116
	v_exp_f32_e32 v119, v119
	v_exp_f32_e32 v121, v120
	v_rcp_f32_e32 v120, v117
	v_add_f32_e32 v117, 1.0, v119
	v_rcp_f32_e32 v119, v117
	v_add_f32_e32 v117, 1.0, v121
	v_mul_f32_e32 v121, v32, v116
	v_exp_f32_e32 v122, v121
	v_mul_f32_e32 v121, v28, v116
	v_exp_f32_e32 v123, v121
	v_rcp_f32_e32 v121, v117
	v_add_f32_e32 v117, 1.0, v122
	v_rcp_f32_e32 v122, v117
	v_add_f32_e32 v117, 1.0, v123
	v_mul_f32_e32 v123, v33, v116
	v_mul_f32_e32 v116, v29, v116
	v_exp_f32_e32 v123, v123
	v_exp_f32_e32 v124, v116
	v_rcp_f32_e32 v116, v117
	v_add_f32_e32 v117, 1.0, v123
	v_rcp_f32_e32 v123, v117
	v_add_f32_e32 v117, 1.0, v124
	v_rcp_f32_e32 v117, v117
	v_lshlrev_b32_e32 v106, 16, v102
	v_and_b32_e32 v107, 0xffff0000, v102
	v_lshlrev_b32_e32 v102, 16, v103
	v_and_b32_e32 v103, 0xffff0000, v103
	v_lshlrev_b32_e32 v108, 16, v104
	v_and_b32_e32 v109, 0xffff0000, v104
	v_lshlrev_b32_e32 v104, 16, v105
	v_and_b32_e32 v105, 0xffff0000, v105
	v_lshlrev_b32_e32 v110, 16, v98
	v_and_b32_e32 v111, 0xffff0000, v98
	v_lshlrev_b32_e32 v98, 16, v99
	v_and_b32_e32 v99, 0xffff0000, v99
	v_lshlrev_b32_e32 v112, 16, v100
	v_and_b32_e32 v113, 0xffff0000, v100
	v_lshlrev_b32_e32 v100, 16, v101
	v_and_b32_e32 v101, 0xffff0000, v101
	v_pk_fma_f32 v[106:107], v[118:119], v[106:107], v[110:111]
	v_pk_fma_f32 v[108:109], v[120:121], v[108:109], v[112:113]
	v_pk_fma_f32 v[102:103], v[122:123], v[102:103], v[98:99]
	v_pk_fma_f32 v[104:105], v[116:117], v[104:105], v[100:101]
	s_mov_b64 s[12:13], -1
	s_and_b64 vcc, exec, s[8:9]
	v_cvt_pk_bf16_f32 v98, v106, v107
	v_cvt_pk_bf16_f32 v99, v102, v103
	v_cvt_pk_bf16_f32 v100, v108, v109
	v_cvt_pk_bf16_f32 v101, v104, v105
	s_cbranch_vccnz .LBB0_1211
	v_add_co_u32_e32 v102, vcc, 0x800000, v114
	s_mov_b64 s[12:13], 0
	s_nop 0
	v_addc_co_u32_e32 v103, vcc, 0, v115, vcc
	global_store_dwordx2 v[102:103], v[98:99], off
	global_store_dwordx2 v[102:103], v[100:101], off offset:512

.LBB0_1213:
	s_nop 1
	v_fmamk_f32 v98, v149, 0x3a800000, v228
	v_mul_f32_e32 v99, 0x4b800000, v98
	v_cmp_gt_f32_e32 vcc, s69, v98
	v_lshlrev_b32_e32 v102, 16, v94
	v_and_b32_e32 v103, 0xffff0000, v94
	v_cndmask_b32_e32 v98, v98, v99, vcc
	v_rsq_f32_e32 v100, v98
	v_lshlrev_b32_e32 v94, 16, v95
	v_and_b32_e32 v95, 0xffff0000, v95
	v_lshlrev_b32_e32 v104, 16, v96
	v_mul_f32_e32 v101, 0x45800000, v100
	v_cndmask_b32_e32 v100, v100, v101, vcc
	v_mul_f32_e32 v100, 0xbfb8aa3b, v100
	v_mul_f32_e32 v101, v38, v100
	v_mul_f32_e32 v110, v34, v100
	v_exp_f32_e32 v101, v101
	v_exp_f32_e32 v111, v110
	v_mul_f32_e32 v112, v35, v100
	v_add_f32_e32 v101, 1.0, v101
	v_rcp_f32_e32 v110, v101
	v_add_f32_e32 v101, 1.0, v111
	v_mul_f32_e32 v111, v39, v100
	v_exp_f32_e32 v111, v111
	v_exp_f32_e32 v113, v112
	v_rcp_f32_e32 v112, v101
	v_add_f32_e32 v101, 1.0, v111
	v_rcp_f32_e32 v111, v101
	v_add_f32_e32 v101, 1.0, v113
	v_mul_f32_e32 v113, v40, v100
	v_exp_f32_e32 v114, v113
	v_mul_f32_e32 v113, v36, v100
	v_exp_f32_e32 v115, v113
	v_rcp_f32_e32 v113, v101
	v_add_f32_e32 v101, 1.0, v114
	v_rcp_f32_e32 v114, v101
	v_add_f32_e32 v101, 1.0, v115
	v_mul_f32_e32 v115, v41, v100
	v_mul_f32_e32 v116, v37, v100
	v_exp_f32_e32 v115, v115
	v_exp_f32_e32 v117, v116
	v_rcp_f32_e32 v116, v101
	v_add_f32_e32 v101, 1.0, v115
	v_rcp_f32_e32 v115, v101
	v_add_f32_e32 v101, 1.0, v117
	v_rcp_f32_e32 v117, v101
	v_and_b32_e32 v105, 0xffff0000, v96
	v_lshlrev_b32_e32 v96, 16, v97
	v_and_b32_e32 v97, 0xffff0000, v97
	v_lshlrev_b32_e32 v106, 16, v90
	v_and_b32_e32 v107, 0xffff0000, v90
	v_lshlrev_b32_e32 v90, 16, v91
	v_and_b32_e32 v91, 0xffff0000, v91
	v_lshlrev_b32_e32 v108, 16, v92
	v_and_b32_e32 v109, 0xffff0000, v92
	v_lshlrev_b32_e32 v92, 16, v93
	v_and_b32_e32 v93, 0xffff0000, v93
	v_pk_fma_f32 v[102:103], v[110:111], v[102:103], v[106:107]
	v_pk_fma_f32 v[104:105], v[112:113], v[104:105], v[108:109]
	v_pk_fma_f32 v[94:95], v[114:115], v[94:95], v[90:91]
	v_pk_fma_f32 v[96:97], v[116:117], v[96:97], v[92:93]
	v_lshl_add_u64 v[98:99], v[142:143], 0, s[38:39]
	v_cvt_pk_bf16_f32 v90, v102, v103
	v_cvt_pk_bf16_f32 v91, v94, v95
	s_mov_b64 s[12:13], -1
	s_and_b64 vcc, exec, s[8:9]
	v_cvt_pk_bf16_f32 v92, v104, v105
	v_cvt_pk_bf16_f32 v93, v96, v97
	s_cbranch_vccnz .LBB0_1215
	s_mov_b64 s[12:13], 0
	global_store_dwordx2 v[98:99], v[90:91], off
	global_store_dwordx2 v[98:99], v[92:93], off offset:512

.LBB0_1217:
	v_mul_f32_e32 v101, v14, v100
	v_mul_f32_e32 v102, v10, v100
	v_exp_f32_e32 v101, v101
	v_exp_f32_e32 v103, v102
	v_mul_f32_e32 v104, v11, v100
	v_add_f32_e32 v101, 1.0, v101
	v_rcp_f32_e32 v102, v101
	v_add_f32_e32 v101, 1.0, v103
	v_mul_f32_e32 v103, v15, v100
	v_exp_f32_e32 v103, v103
	v_exp_f32_e32 v105, v104
	v_rcp_f32_e32 v104, v101
	v_add_f32_e32 v101, 1.0, v103
	v_rcp_f32_e32 v103, v101
	v_add_f32_e32 v101, 1.0, v105
	v_mul_f32_e32 v105, v16, v100
	v_exp_f32_e32 v106, v105
	v_mul_f32_e32 v105, v12, v100
	v_exp_f32_e32 v107, v105
	v_rcp_f32_e32 v105, v101
	v_add_f32_e32 v101, 1.0, v106
	v_rcp_f32_e32 v106, v101
	v_add_f32_e32 v101, 1.0, v107
	v_mul_f32_e32 v107, v17, v100
	v_mul_f32_e32 v100, v13, v100
	v_exp_f32_e32 v107, v107
	v_exp_f32_e32 v108, v100
	v_rcp_f32_e32 v100, v101
	v_add_f32_e32 v101, 1.0, v107
	v_rcp_f32_e32 v107, v101
	v_add_f32_e32 v101, 1.0, v108
	v_rcp_f32_e32 v101, v101
	v_lshlrev_b32_e32 v90, 16, v86
	v_and_b32_e32 v91, 0xffff0000, v86
	v_lshlrev_b32_e32 v86, 16, v87
	v_and_b32_e32 v87, 0xffff0000, v87
	v_lshlrev_b32_e32 v92, 16, v88
	v_and_b32_e32 v93, 0xffff0000, v88
	v_lshlrev_b32_e32 v88, 16, v89
	v_and_b32_e32 v89, 0xffff0000, v89
	v_lshlrev_b32_e32 v94, 16, v82
	v_and_b32_e32 v95, 0xffff0000, v82
	v_lshlrev_b32_e32 v82, 16, v83
	v_and_b32_e32 v83, 0xffff0000, v83
	v_lshlrev_b32_e32 v96, 16, v84
	v_and_b32_e32 v97, 0xffff0000, v84
	v_lshlrev_b32_e32 v84, 16, v85
	v_and_b32_e32 v85, 0xffff0000, v85
	v_pk_fma_f32 v[90:91], v[102:103], v[90:91], v[94:95]
	v_pk_fma_f32 v[92:93], v[104:105], v[92:93], v[96:97]
	v_pk_fma_f32 v[86:87], v[106:107], v[86:87], v[82:83]
	v_pk_fma_f32 v[88:89], v[100:101], v[88:89], v[84:85]
	s_mov_b64 s[12:13], -1
	s_and_b64 vcc, exec, s[8:9]
	v_cvt_pk_bf16_f32 v82, v90, v91
	v_cvt_pk_bf16_f32 v83, v86, v87
	v_cvt_pk_bf16_f32 v84, v92, v93
	v_cvt_pk_bf16_f32 v85, v88, v89
	s_cbranch_vccnz .LBB0_1219
	v_add_co_u32_e32 v86, vcc, 0x800000, v98
	s_mov_b64 s[12:13], 0
	s_nop 0
	v_addc_co_u32_e32 v87, vcc, 0, v99, vcc
	global_store_dwordx2 v[86:87], v[82:83], off
	global_store_dwordx2 v[86:87], v[84:85], off offset:512

.LBB0_1221:
	s_nop 1
	v_fmamk_f32 v82, v148, 0x3a800000, v228
	v_mul_f32_e32 v83, 0x4b800000, v82
	v_cmp_gt_f32_e32 vcc, s69, v82
	s_lshl_b64 s[12:13], s[36:37], 1
	s_add_u32 s12, s43, s12
	v_cndmask_b32_e32 v82, v82, v83, vcc
	v_rsq_f32_e32 v82, v82
	s_addc_u32 s13, s41, s13
	v_lshlrev_b32_e32 v86, 16, v78
	v_and_b32_e32 v87, 0xffff0000, v78
	v_mul_f32_e32 v83, 0x45800000, v82
	v_cndmask_b32_e32 v84, v82, v83, vcc
	v_mul_f32_e32 v84, 0xbfb8aa3b, v84
	v_mul_f32_e32 v85, v22, v84
	v_mul_f32_e32 v94, v18, v84
	v_exp_f32_e32 v85, v85
	v_exp_f32_e32 v95, v94
	v_mul_f32_e32 v96, v19, v84
	v_add_f32_e32 v85, 1.0, v85
	v_rcp_f32_e32 v94, v85
	v_add_f32_e32 v85, 1.0, v95
	v_mul_f32_e32 v95, v23, v84
	v_exp_f32_e32 v95, v95
	v_exp_f32_e32 v97, v96
	v_rcp_f32_e32 v96, v85
	v_add_f32_e32 v85, 1.0, v95
	v_rcp_f32_e32 v95, v85
	v_add_f32_e32 v85, 1.0, v97
	v_mul_f32_e32 v97, v24, v84
	v_exp_f32_e32 v98, v97
	v_mul_f32_e32 v97, v20, v84
	v_exp_f32_e32 v99, v97
	v_rcp_f32_e32 v97, v85
	v_add_f32_e32 v85, 1.0, v98
	v_rcp_f32_e32 v98, v85
	v_add_f32_e32 v85, 1.0, v99
	v_mul_f32_e32 v99, v25, v84
	v_mul_f32_e32 v100, v21, v84
	v_exp_f32_e32 v99, v99
	v_exp_f32_e32 v101, v100
	v_rcp_f32_e32 v100, v85
	v_add_f32_e32 v85, 1.0, v99
	v_rcp_f32_e32 v99, v85
	v_add_f32_e32 v85, 1.0, v101
	v_rcp_f32_e32 v101, v85
	v_lshlrev_b32_e32 v78, 16, v79
	v_and_b32_e32 v79, 0xffff0000, v79
	v_lshlrev_b32_e32 v88, 16, v80
	v_and_b32_e32 v89, 0xffff0000, v80
	v_lshlrev_b32_e32 v80, 16, v81
	v_and_b32_e32 v81, 0xffff0000, v81
	v_lshlrev_b32_e32 v90, 16, v74
	v_and_b32_e32 v91, 0xffff0000, v74
	v_lshlrev_b32_e32 v74, 16, v75
	v_and_b32_e32 v75, 0xffff0000, v75
	v_lshlrev_b32_e32 v92, 16, v76
	v_and_b32_e32 v93, 0xffff0000, v76
	v_lshlrev_b32_e32 v76, 16, v77
	v_and_b32_e32 v77, 0xffff0000, v77
	v_lshl_add_u64 v[82:83], v[200:201], 1, s[12:13]
	v_pk_fma_f32 v[86:87], v[94:95], v[86:87], v[90:91]
	v_pk_fma_f32 v[88:89], v[96:97], v[88:89], v[92:93]
	v_pk_fma_f32 v[78:79], v[98:99], v[78:79], v[74:75]
	v_pk_fma_f32 v[80:81], v[100:101], v[80:81], v[76:77]
	v_lshl_add_u64 v[82:83], v[202:203], 1, v[82:83]
	v_cvt_pk_bf16_f32 v74, v86, v87
	v_cvt_pk_bf16_f32 v75, v78, v79
	s_mov_b64 s[12:13], -1
	s_and_b64 vcc, exec, s[8:9]
	v_cvt_pk_bf16_f32 v76, v88, v89
	v_cvt_pk_bf16_f32 v77, v80, v81
	s_cbranch_vccnz .LBB0_1223
	s_mov_b64 s[12:13], 0
	global_store_dwordx2 v[82:83], v[74:75], off
	global_store_dwordx2 v[82:83], v[76:77], off offset:512

.LBB0_1225:
	v_mul_f32_e32 v85, v6, v84
	v_mul_f32_e32 v86, v2, v84
	v_exp_f32_e32 v85, v85
	v_exp_f32_e32 v87, v86
	v_mul_f32_e32 v88, v3, v84
	v_add_f32_e32 v85, 1.0, v85
	v_rcp_f32_e32 v86, v85
	v_add_f32_e32 v85, 1.0, v87
	v_mul_f32_e32 v87, v7, v84
	v_exp_f32_e32 v87, v87
	v_exp_f32_e32 v89, v88
	v_rcp_f32_e32 v88, v85
	v_add_f32_e32 v85, 1.0, v87
	v_rcp_f32_e32 v87, v85
	v_add_f32_e32 v85, 1.0, v89
	v_mul_f32_e32 v89, v8, v84
	v_exp_f32_e32 v90, v89
	v_mul_f32_e32 v89, v4, v84
	v_exp_f32_e32 v91, v89
	v_rcp_f32_e32 v89, v85
	v_add_f32_e32 v85, 1.0, v90
	v_rcp_f32_e32 v90, v85
	v_add_f32_e32 v85, 1.0, v91
	v_mul_f32_e32 v91, v9, v84
	v_mul_f32_e32 v84, v5, v84
	v_exp_f32_e32 v91, v91
	v_exp_f32_e32 v92, v84
	v_rcp_f32_e32 v84, v85
	v_add_f32_e32 v85, 1.0, v91
	v_rcp_f32_e32 v91, v85
	v_add_f32_e32 v85, 1.0, v92
	v_rcp_f32_e32 v85, v85
	v_lshlrev_b32_e32 v74, 16, v70
	v_and_b32_e32 v75, 0xffff0000, v70
	v_lshlrev_b32_e32 v70, 16, v71
	v_and_b32_e32 v71, 0xffff0000, v71
	v_lshlrev_b32_e32 v76, 16, v72
	v_and_b32_e32 v77, 0xffff0000, v72
	v_lshlrev_b32_e32 v72, 16, v73
	v_and_b32_e32 v73, 0xffff0000, v73
	v_lshlrev_b32_e32 v78, 16, v66
	v_and_b32_e32 v79, 0xffff0000, v66
	v_lshlrev_b32_e32 v66, 16, v67
	v_and_b32_e32 v67, 0xffff0000, v67
	v_lshlrev_b32_e32 v80, 16, v68
	v_and_b32_e32 v81, 0xffff0000, v68
	v_lshlrev_b32_e32 v68, 16, v69
	v_and_b32_e32 v69, 0xffff0000, v69
	v_pk_fma_f32 v[74:75], v[86:87], v[74:75], v[78:79]
	v_pk_fma_f32 v[76:77], v[88:89], v[76:77], v[80:81]
	v_pk_fma_f32 v[70:71], v[90:91], v[70:71], v[66:67]
	v_pk_fma_f32 v[72:73], v[84:85], v[72:73], v[68:69]
	s_mov_b64 s[12:13], -1
	s_and_b64 vcc, exec, s[8:9]
	v_cvt_pk_bf16_f32 v66, v74, v75
	v_cvt_pk_bf16_f32 v67, v70, v71
	v_cvt_pk_bf16_f32 v68, v76, v77
	v_cvt_pk_bf16_f32 v69, v72, v73
	s_cbranch_vccnz .LBB0_1227
	v_add_co_u32_e32 v70, vcc, 0x800000, v82
	s_mov_b64 s[12:13], 0
	s_nop 0
	v_addc_co_u32_e32 v71, vcc, 0, v83, vcc
	global_store_dwordx2 v[70:71], v[66:67], off
	global_store_dwordx2 v[70:71], v[68:69], off offset:512
